# own: next item's K/V tile fetched during the current item's epilogue (register-staged, first item at phase entry)
# speedup vs baseline: 1.0033x; 1.0033x over previous
.LBB0_275:
	s_or_b64 exec, exec, s[0:1]
	s_and_b64 vcc, exec, s[82:83]
	s_barrier
	s_cbranch_vccnz .LBB0_298
	s_waitcnt vmcnt(3)
	v_lshlrev_b32_e32 v1, 3, v188
	v_and_b32_e32 v0, 56, v1
	s_waitcnt vmcnt(0)
	v_and_b32_e32 v4, 0xf8, v1
	v_mul_u32_u24_e32 v1, 0x90, v194
	v_lshlrev_b32_e32 v3, 1, v0
	v_add3_u32 v175, 0, v1, v3
	v_mul_u32_u24_e32 v1, 0x90, v123
	v_add3_u32 v123, 0, v1, v3
	v_mul_u32_u24_e32 v1, 0x90, v182
	v_add3_u32 v176, 0, v1, v3
	v_mul_u32_u24_e32 v1, 0x90, v183
	v_add3_u32 v177, 0, v1, v3
	v_mul_u32_u24_e32 v1, 0x210, v197
	v_lshlrev_b32_e32 v3, 1, v4
	v_add3_u32 v182, 0, v1, v3
	v_mul_u32_u24_e32 v1, 0x210, v109
	v_add3_u32 v183, 0, v1, v3
	v_mul_u32_u24_e32 v1, 0x210, v111
	v_mov_b32_e32 v121, 0
	v_add3_u32 v185, 0, v1, v3
	v_mul_u32_u24_e32 v1, 0x210, v113
	v_lshlrev_b32_e32 v174, 5, v196
	v_add3_u32 v186, 0, v1, v3
	v_mul_u32_u24_e32 v1, 0x90, v146
	v_mul_u32_u24_e32 v3, 0x210, v146
	v_mov_b32_e32 v125, v121
	v_lshlrev_b32_e32 v5, 7, v146
	v_lshlrev_b32_e32 v2, 12, v197
	v_lshlrev_b32_e32 v6, 12, v109
	v_lshlrev_b32_e32 v8, 12, v111
	v_lshlrev_b32_e32 v10, 12, v113
	v_or_b32_e32 v48, v174, v146
	v_lshl_add_u64 v[12:13], s[64:65], 0, v[124:125]
	v_lshl_or_b32 v14, v196, 12, v5
	v_mov_b32_e32 v15, v121
	v_add3_u32 v187, v1, v124, 0
	v_add3_u32 v1, v3, v120, 0
	s_mov_b32 s13, 0
	v_cmp_eq_u32_e64 s[8:9], 0, v184
	v_cmp_gt_u32_e64 s[10:11], 2, v181
	v_or_b32_e32 v184, 31, v174
	v_or_b32_e32 v49, 16, v48
	v_lshl_add_u64 v[50:51], v[12:13], 0, v[14:15]
	v_lshl_add_u64 v[52:53], s[50:51], 0, v[120:121]
	v_mov_b32_e32 v54, v48
	v_mov_b32_e32 v55, v48
	v_add_u32_e32 v197, 0x9000, v1
	v_lshlrev_b32_e32 v56, 1, v112
	v_lshlrev_b32_e32 v58, 1, v0
	v_lshlrev_b32_e32 v60, 1, v108
	v_lshlrev_b32_e32 v62, 1, v110
	v_lshlrev_b32_e32 v120, 1, v114
	v_lshlrev_b32_e32 v64, 1, v2
	v_lshlrev_b32_e32 v66, 1, v4
	v_lshlrev_b32_e32 v68, 1, v6
	v_lshlrev_b32_e32 v70, 1, v8
	v_lshlrev_b32_e32 v72, 1, v10
	s_movk_i32 s4, 0x180
	s_mov_b32 s5, 0xf149f2ca
	s_mov_b32 s22, 0xefa18f08
	v_lshlrev_b32_e32 v74, 1, v122
	v_mov_b32_e32 v57, v121
	v_mov_b32_e32 v59, v121
	v_mov_b32_e32 v61, v121
	v_mov_b32_e32 v63, v121
	v_mov_b32_e32 v198, 0xf149f2ca
	s_mov_b32 s23, s2
	s_mov_b32 s25, s2
	s_ashr_i32 s26, s25, 4
	s_and_b32 s30, s25, 15
	s_ashr_i32 s27, s26, 31
	s_lshl_b64 s[28:29], s[26:27], 12
	s_lshl_b32 s31, s30, 8
	s_or_b32 s32, s28, s31
	s_mov_b32 s33, s29
	s_lshl_b64 s[32:33], s[32:33], 7
	s_add_u32 s34, s66, s32
	s_addc_u32 s35, s67, s33
	s_lshl_b64 s[40:41], s[26:27], 19
	s_add_u32 s27, s68, s40
	s_addc_u32 s41, s69, s41
	s_lshl_b32 s40, s30, 9
	s_add_u32 s40, s27, s40
	s_addc_u32 s41, s41, 0
	v_mov_b32_e32 v233, 0
	v_add_u32_e32 v232, v56, v58
	v_lshl_add_u64 v[200:201], s[34:35], 0, v[232:233]
	v_add_u32_e32 v232, v60, v58
	v_lshl_add_u64 v[204:205], s[34:35], 0, v[232:233]
	v_add_u32_e32 v232, v62, v58
	v_lshl_add_u64 v[208:209], s[34:35], 0, v[232:233]
	v_add_u32_e32 v232, v120, v58
	v_lshl_add_u64 v[212:213], s[34:35], 0, v[232:233]
	v_add_u32_e32 v232, v64, v66
	v_lshl_add_u64 v[216:217], s[40:41], 0, v[232:233]
	v_add_u32_e32 v232, v68, v66
	v_lshl_add_u64 v[220:221], s[40:41], 0, v[232:233]
	v_add_u32_e32 v232, v70, v66
	v_lshl_add_u64 v[224:225], s[40:41], 0, v[232:233]
	v_add_u32_e32 v232, v72, v66
	v_lshl_add_u64 v[228:229], s[40:41], 0, v[232:233]
	global_load_dwordx4 v[200:203], v[200:201], off
	global_load_dwordx4 v[204:207], v[204:205], off
	global_load_dwordx4 v[208:211], v[208:209], off
	global_load_dwordx4 v[212:215], v[212:213], off
	global_load_dwordx4 v[216:219], v[216:217], off
	global_load_dwordx4 v[220:223], v[220:221], off
	global_load_dwordx4 v[224:227], v[224:225], off
	global_load_dwordx4 v[228:231], v[228:229], off
	s_branch .LBB0_278
.LBB0_277:
	s_ashr_i32 s0, s23, 7
	s_ashr_i32 s1, s0, 31
	s_lshl_b64 s[0:1], s[0:1], 22
	s_waitcnt vmcnt(0)
	v_lshlrev_b32_e32 v20, 10, v140
	v_mov_b32_e32 v21, v121
	v_lshl_add_u64 v[20:21], s[0:1], 0, v[20:21]
	v_lshlrev_b64 v[20:21], 1, v[20:21]
	s_lshl_b32 s0, s14, 7
	v_lshl_add_u64 v[22:23], s[70:71], 0, v[20:21]
	s_and_b32 s12, s0, 0x380
	v_lshl_add_u64 v[22:23], v[22:23], 0, s[12:13]
	v_mov_b32_e32 v75, v121
	v_lshl_add_u64 v[140:141], v[22:23], 0, v[74:75]
	s_mov_b64 s[72:73], 0x8000
	global_load_dwordx2 v[234:235], v[140:141], off offset:1024
	global_load_dwordx2 v[236:237], v[140:141], off offset:1056
	global_load_dwordx2 v[238:239], v[140:141], off offset:1088
	global_load_dwordx2 v[240:241], v[140:141], off offset:1120
	v_lshl_add_u64 v[250:251], v[140:141], 0, s[72:73]
	global_load_dwordx2 v[242:243], v[250:251], off offset:1024
	global_load_dwordx2 v[244:245], v[250:251], off offset:1056
	global_load_dwordx2 v[246:247], v[250:251], off offset:1088
	global_load_dwordx2 v[248:249], v[250:251], off offset:1120
	s_add_i32 s25, s23, s3
	s_min_i32 s25, s25, 0x7ff
	s_ashr_i32 s26, s25, 4
	s_and_b32 s30, s25, 15
	s_ashr_i32 s27, s26, 31
	s_lshl_b64 s[28:29], s[26:27], 12
	s_lshl_b32 s31, s30, 8
	s_or_b32 s32, s28, s31
	s_mov_b32 s33, s29
	s_lshl_b64 s[32:33], s[32:33], 7
	s_add_u32 s34, s66, s32
	s_addc_u32 s35, s67, s33
	s_lshl_b64 s[40:41], s[26:27], 19
	s_add_u32 s27, s68, s40
	s_addc_u32 s41, s69, s41
	s_lshl_b32 s40, s30, 9
	s_add_u32 s40, s27, s40
	s_addc_u32 s41, s41, 0
	v_mov_b32_e32 v233, 0
	v_add_u32_e32 v232, v56, v58
	v_lshl_add_u64 v[200:201], s[34:35], 0, v[232:233]
	v_add_u32_e32 v232, v60, v58
	v_lshl_add_u64 v[204:205], s[34:35], 0, v[232:233]
	v_add_u32_e32 v232, v62, v58
	v_lshl_add_u64 v[208:209], s[34:35], 0, v[232:233]
	v_add_u32_e32 v232, v120, v58
	v_lshl_add_u64 v[212:213], s[34:35], 0, v[232:233]
	v_add_u32_e32 v232, v64, v66
	v_lshl_add_u64 v[216:217], s[40:41], 0, v[232:233]
	v_add_u32_e32 v232, v68, v66
	v_lshl_add_u64 v[220:221], s[40:41], 0, v[232:233]
	v_add_u32_e32 v232, v70, v66
	v_lshl_add_u64 v[224:225], s[40:41], 0, v[232:233]
	v_add_u32_e32 v232, v72, v66
	v_lshl_add_u64 v[228:229], s[40:41], 0, v[232:233]
	global_load_dwordx4 v[200:203], v[200:201], off
	global_load_dwordx4 v[204:207], v[204:205], off
	global_load_dwordx4 v[208:211], v[208:209], off
	global_load_dwordx4 v[212:215], v[212:213], off
	global_load_dwordx4 v[216:219], v[216:217], off
	global_load_dwordx4 v[220:223], v[220:221], off
	global_load_dwordx4 v[224:227], v[224:225], off
	global_load_dwordx4 v[228:231], v[228:229], off
	v_max_f32_e32 v22, v132, v132
	v_max_f32_e32 v23, v71, v71
	v_max_f32_e32 v30, v23, v22
	v_sub_f32_e32 v22, v71, v30
	v_sub_f32_e32 v23, v132, v30
	v_exp_f32_e32 v22, v22
	v_exp_f32_e32 v23, v23
	v_max_f32_e32 v24, v148, v148
	v_max_f32_e32 v24, v30, v24
	v_mov_b32_e32 v132, v114
	v_sub_f32_e32 v30, v30, v24
	v_exp_f32_e32 v139, v30
	v_pk_mul_f32 v[30:31], v[132:133], v[22:23]
	v_sub_f32_e32 v65, v148, v24
	v_pk_fma_f32 v[132:133], v[132:133], v[22:23], v[30:31] op_sel_hi:[1,1,0]
	v_lshlrev_b32_e32 v26, 16, v142
	v_exp_f32_e32 v132, v65
	v_and_b32_e32 v27, 0xffff0000, v142
	v_lshlrev_b32_e32 v28, 16, v143
	v_and_b32_e32 v29, 0xffff0000, v143
	v_max_f32_e32 v25, v152, v152
	v_pk_mul_f32 v[32:33], v[30:31], v[26:27] op_sel:[1,0]
	v_max_f32_e32 v25, v24, v25
	v_mov_b32_e32 v26, v139
	v_pk_mul_f32 v[148:149], v[30:31], v[28:29] op_sel:[1,0]
	v_pk_fma_f32 v[32:33], v[44:45], v[22:23], v[32:33] op_sel_hi:[1,0,1]
	v_sub_f32_e32 v24, v24, v25
	v_pk_fma_f32 v[44:45], v[46:47], v[22:23], v[148:149] op_sel_hi:[1,0,1]
	v_pk_mul_f32 v[46:47], v[26:27], v[32:33] op_sel_hi:[0,1]
	v_pk_mul_f32 v[32:33], v[138:139], v[132:133]
	v_sub_f32_e32 v67, v152, v25
	v_exp_f32_e32 v137, v24
	v_pk_fma_f32 v[132:133], v[138:139], v[132:133], v[32:33] op_sel_hi:[1,1,0]
	v_lshlrev_b32_e32 v34, 16, v150
	v_exp_f32_e32 v132, v67
	v_and_b32_e32 v35, 0xffff0000, v150
	v_mov_b32_e32 v28, v137
	v_pk_fma_f32 v[34:35], v[32:33], v[34:35], v[46:47] op_sel_hi:[0,1,1]
	v_pk_mul_f32 v[138:139], v[28:29], v[34:35] op_sel_hi:[0,1]
	v_pk_mul_f32 v[34:35], v[136:137], v[132:133]
	v_lshlrev_b32_e32 v142, 16, v151
	v_and_b32_e32 v143, 0xffff0000, v151
	v_pk_mul_f32 v[44:45], v[26:27], v[44:45] op_sel_hi:[0,1]
	v_add_f32_e32 v23, v34, v35
	v_pk_fma_f32 v[46:47], v[32:33], v[142:143], v[44:45] op_sel_hi:[0,1,1]
	v_rcp_f32_e32 v44, v23
	v_lshlrev_b32_e32 v150, 16, v154
	v_and_b32_e32 v151, 0xffff0000, v154
	v_lshlrev_b32_e32 v154, 16, v155
	v_and_b32_e32 v155, 0xffff0000, v155
	v_pk_mul_f32 v[46:47], v[28:29], v[46:47] op_sel_hi:[0,1]
	v_pk_fma_f32 v[132:133], v[34:35], v[150:151], v[138:139] op_sel_hi:[0,1,1]
	v_pk_fma_f32 v[46:47], v[34:35], v[154:155], v[46:47] op_sel_hi:[0,1,1]
	v_pk_mul_f32 v[132:133], v[44:45], v[132:133] op_sel_hi:[0,1]
	v_pk_mul_f32 v[46:47], v[44:45], v[46:47] op_sel_hi:[0,1]
	v_readlane_b32 s16, v254, 2
	v_readlane_b32 s17, v254, 3
	s_add_i32 s23, s23, s3
	s_cmpk_lt_i32 s23, 0x800
	v_lshl_add_u64 v[24:25], s[16:17], 0, v[20:21]
	v_lshl_add_u64 v[24:25], v[24:25], 0, s[12:13]
	v_lshl_add_u64 v[24:25], v[24:25], 0, v[74:75]
	v_or_b32_e32 v20, 0x8000, v20
	v_readlane_b32 s18, v254, 4
	v_readlane_b32 s19, v254, 5
	s_waitcnt vmcnt(15)
	v_mov_b32_e32 v156, v234
	v_mov_b32_e32 v157, v235
	v_lshlrev_b32_e32 v136, 16, v156
	v_and_b32_e32 v137, 0xffff0000, v156
	v_lshlrev_b32_e32 v138, 16, v157
	v_and_b32_e32 v139, 0xffff0000, v157
	v_mul_f32_e32 v23, 0xbfb8aa3b, v136
	v_mul_f32_e32 v27, 0xbfb8aa3b, v137
	v_mul_f32_e32 v29, 0xbfb8aa3b, v138
	v_mul_f32_e32 v45, 0xbfb8aa3b, v139
	v_exp_f32_e32 v23, v23
	v_exp_f32_e32 v27, v27
	v_exp_f32_e32 v29, v29
	v_exp_f32_e32 v45, v45
	v_add_f32_e32 v23, 1.0, v23
	v_add_f32_e32 v27, 1.0, v27
	v_add_f32_e32 v29, 1.0, v29
	v_add_f32_e32 v45, 1.0, v45
	v_rcp_f32_e32 v142, v23
	v_rcp_f32_e32 v143, v27
	v_rcp_f32_e32 v148, v29
	v_rcp_f32_e32 v149, v45
	v_pk_mul_f32 v[132:133], v[132:133], v[136:137]
	v_pk_mul_f32 v[46:47], v[46:47], v[138:139]
	v_pk_mul_f32 v[132:133], v[132:133], v[142:143]
	v_pk_mul_f32 v[46:47], v[46:47], v[148:149]
	v_cvt_pk_bf16_f32 v132, v132, v133
	v_cvt_pk_bf16_f32 v133, v46, v47
	global_store_dwordx2 v[24:25], v[132:133], off offset:1024
	v_lshlrev_b32_e32 v132, 16, v128
	v_and_b32_e32 v133, 0xffff0000, v128
	v_lshlrev_b32_e32 v128, 16, v129
	v_and_b32_e32 v129, 0xffff0000, v129
	v_pk_mul_f32 v[132:133], v[30:31], v[132:133] op_sel:[1,0]
	v_pk_mul_f32 v[128:129], v[30:31], v[128:129] op_sel:[1,0]
	v_pk_fma_f32 v[40:41], v[40:41], v[22:23], v[132:133] op_sel_hi:[1,0,1]
	v_pk_fma_f32 v[42:43], v[42:43], v[22:23], v[128:129] op_sel_hi:[1,0,1]
	v_lshlrev_b32_e32 v136, 16, v130
	v_and_b32_e32 v137, 0xffff0000, v130
	v_lshlrev_b32_e32 v130, 16, v131
	v_and_b32_e32 v131, 0xffff0000, v131
	v_pk_mul_f32 v[40:41], v[26:27], v[40:41] op_sel_hi:[0,1]
	v_pk_mul_f32 v[42:43], v[26:27], v[42:43] op_sel_hi:[0,1]
	v_pk_fma_f32 v[40:41], v[32:33], v[136:137], v[40:41] op_sel_hi:[0,1,1]
	v_pk_fma_f32 v[42:43], v[32:33], v[130:131], v[42:43] op_sel_hi:[0,1,1]
	v_lshlrev_b32_e32 v138, 16, v134
	v_and_b32_e32 v139, 0xffff0000, v134
	v_lshlrev_b32_e32 v134, 16, v135
	v_and_b32_e32 v135, 0xffff0000, v135
	v_pk_mul_f32 v[40:41], v[28:29], v[40:41] op_sel_hi:[0,1]
	v_pk_mul_f32 v[42:43], v[28:29], v[42:43] op_sel_hi:[0,1]
	v_pk_fma_f32 v[40:41], v[34:35], v[138:139], v[40:41] op_sel_hi:[0,1,1]
	v_pk_fma_f32 v[42:43], v[34:35], v[134:135], v[42:43] op_sel_hi:[0,1,1]
	v_pk_mul_f32 v[40:41], v[44:45], v[40:41] op_sel_hi:[0,1]
	v_pk_mul_f32 v[42:43], v[44:45], v[42:43] op_sel_hi:[0,1]
	s_waitcnt vmcnt(15)
	v_mov_b32_e32 v46, v236
	v_mov_b32_e32 v47, v237
	v_lshlrev_b32_e32 v128, 16, v46
	v_and_b32_e32 v129, 0xffff0000, v46
	v_lshlrev_b32_e32 v46, 16, v47
	v_and_b32_e32 v47, 0xffff0000, v47
	v_mul_f32_e32 v23, 0xbfb8aa3b, v128
	v_mul_f32_e32 v27, 0xbfb8aa3b, v129
	v_mul_f32_e32 v29, 0xbfb8aa3b, v46
	v_mul_f32_e32 v45, 0xbfb8aa3b, v47
	v_exp_f32_e32 v23, v23
	v_exp_f32_e32 v27, v27
	v_exp_f32_e32 v29, v29
	v_exp_f32_e32 v45, v45
	v_add_f32_e32 v23, 1.0, v23
	v_add_f32_e32 v27, 1.0, v27
	v_add_f32_e32 v29, 1.0, v29
	v_add_f32_e32 v45, 1.0, v45
	v_rcp_f32_e32 v130, v23
	v_rcp_f32_e32 v131, v27
	v_rcp_f32_e32 v132, v29
	v_rcp_f32_e32 v133, v45
	v_pk_mul_f32 v[40:41], v[40:41], v[128:129]
	v_pk_mul_f32 v[42:43], v[42:43], v[46:47]
	v_pk_mul_f32 v[40:41], v[40:41], v[130:131]
	v_pk_mul_f32 v[42:43], v[42:43], v[132:133]
	v_cvt_pk_bf16_f32 v40, v40, v41
	v_cvt_pk_bf16_f32 v41, v42, v43
	global_store_dwordx2 v[24:25], v[40:41], off offset:1056
	v_lshlrev_b32_e32 v42, 16, v118
	v_and_b32_e32 v43, 0xffff0000, v118
	v_lshlrev_b32_e32 v46, 16, v119
	v_and_b32_e32 v47, 0xffff0000, v119
	v_pk_mul_f32 v[42:43], v[30:31], v[42:43] op_sel:[1,0]
	v_pk_mul_f32 v[46:47], v[30:31], v[46:47] op_sel:[1,0]
	v_pk_fma_f32 v[36:37], v[36:37], v[22:23], v[42:43] op_sel_hi:[1,0,1]
	v_pk_fma_f32 v[38:39], v[38:39], v[22:23], v[46:47] op_sel_hi:[1,0,1]
	v_lshlrev_b32_e32 v118, 16, v124
	v_and_b32_e32 v119, 0xffff0000, v124
	v_lshlrev_b32_e32 v124, 16, v125
	v_and_b32_e32 v125, 0xffff0000, v125
	v_pk_mul_f32 v[36:37], v[26:27], v[36:37] op_sel_hi:[0,1]
	v_pk_mul_f32 v[38:39], v[26:27], v[38:39] op_sel_hi:[0,1]
	v_pk_fma_f32 v[36:37], v[32:33], v[118:119], v[36:37] op_sel_hi:[0,1,1]
	v_pk_fma_f32 v[38:39], v[32:33], v[124:125], v[38:39] op_sel_hi:[0,1,1]
	v_lshlrev_b32_e32 v128, 16, v126
	v_and_b32_e32 v129, 0xffff0000, v126
	v_lshlrev_b32_e32 v126, 16, v127
	v_and_b32_e32 v127, 0xffff0000, v127
	v_pk_mul_f32 v[36:37], v[28:29], v[36:37] op_sel_hi:[0,1]
	v_pk_mul_f32 v[38:39], v[28:29], v[38:39] op_sel_hi:[0,1]
	v_pk_fma_f32 v[36:37], v[34:35], v[128:129], v[36:37] op_sel_hi:[0,1,1]
	v_pk_fma_f32 v[38:39], v[34:35], v[126:127], v[38:39] op_sel_hi:[0,1,1]
	v_pk_mul_f32 v[36:37], v[44:45], v[36:37] op_sel_hi:[0,1]
	v_pk_mul_f32 v[38:39], v[44:45], v[38:39] op_sel_hi:[0,1]
	s_waitcnt vmcnt(15)
	v_mov_b32_e32 v40, v238
	v_mov_b32_e32 v41, v239
	v_lshlrev_b32_e32 v42, 16, v40
	v_and_b32_e32 v43, 0xffff0000, v40
	v_lshlrev_b32_e32 v40, 16, v41
	v_and_b32_e32 v41, 0xffff0000, v41
	v_mul_f32_e32 v23, 0xbfb8aa3b, v42
	v_mul_f32_e32 v27, 0xbfb8aa3b, v43
	v_mul_f32_e32 v29, 0xbfb8aa3b, v40
	v_mul_f32_e32 v45, 0xbfb8aa3b, v41
	v_exp_f32_e32 v23, v23
	v_exp_f32_e32 v27, v27
	v_exp_f32_e32 v29, v29
	v_exp_f32_e32 v45, v45
	v_add_f32_e32 v23, 1.0, v23
	v_add_f32_e32 v27, 1.0, v27
	v_add_f32_e32 v29, 1.0, v29
	v_add_f32_e32 v45, 1.0, v45
	v_rcp_f32_e32 v46, v23
	v_rcp_f32_e32 v47, v27
	v_rcp_f32_e32 v118, v29
	v_rcp_f32_e32 v119, v45
	v_pk_mul_f32 v[36:37], v[36:37], v[42:43]
	v_pk_mul_f32 v[38:39], v[38:39], v[40:41]
	v_pk_mul_f32 v[36:37], v[36:37], v[46:47]
	v_pk_mul_f32 v[38:39], v[38:39], v[118:119]
	v_cvt_pk_bf16_f32 v36, v36, v37
	v_cvt_pk_bf16_f32 v37, v38, v39
	global_store_dwordx2 v[24:25], v[36:37], off offset:1088
	v_lshlrev_b32_e32 v38, 16, v112
	v_and_b32_e32 v39, 0xffff0000, v112
	v_lshlrev_b32_e32 v40, 16, v113
	v_and_b32_e32 v41, 0xffff0000, v113
	v_pk_mul_f32 v[38:39], v[30:31], v[38:39] op_sel:[1,0]
	v_pk_mul_f32 v[40:41], v[30:31], v[40:41] op_sel:[1,0]
	v_pk_fma_f32 v[16:17], v[16:17], v[22:23], v[38:39] op_sel_hi:[1,0,1]
	v_pk_fma_f32 v[18:19], v[18:19], v[22:23], v[40:41] op_sel_hi:[1,0,1]
	v_lshlrev_b32_e32 v42, 16, v110
	v_and_b32_e32 v43, 0xffff0000, v110
	v_lshlrev_b32_e32 v46, 16, v111
	v_and_b32_e32 v47, 0xffff0000, v111
	v_pk_mul_f32 v[16:17], v[26:27], v[16:17] op_sel_hi:[0,1]
	v_pk_mul_f32 v[18:19], v[26:27], v[18:19] op_sel_hi:[0,1]
	v_pk_fma_f32 v[16:17], v[32:33], v[42:43], v[16:17] op_sel_hi:[0,1,1]
	v_pk_fma_f32 v[18:19], v[32:33], v[46:47], v[18:19] op_sel_hi:[0,1,1]
	v_pk_mul_f32 v[16:17], v[28:29], v[16:17] op_sel_hi:[0,1]
	v_pk_mul_f32 v[18:19], v[28:29], v[18:19] op_sel_hi:[0,1]
	v_lshlrev_b32_e32 v110, 16, v116
	v_and_b32_e32 v111, 0xffff0000, v116
	v_lshlrev_b32_e32 v112, 16, v117
	v_and_b32_e32 v113, 0xffff0000, v117
	v_pk_fma_f32 v[16:17], v[34:35], v[110:111], v[16:17] op_sel_hi:[0,1,1]
	v_pk_fma_f32 v[18:19], v[34:35], v[112:113], v[18:19] op_sel_hi:[0,1,1]
	v_pk_mul_f32 v[16:17], v[44:45], v[16:17] op_sel_hi:[0,1]
	v_pk_mul_f32 v[18:19], v[44:45], v[18:19] op_sel_hi:[0,1]
	v_lshl_add_u64 v[116:117], s[70:71], 0, v[20:21]
	v_lshl_add_u64 v[116:117], v[116:117], 0, s[12:13]
	v_lshl_add_u64 v[30:31], v[116:117], 0, v[74:75]
	v_lshlrev_b32_e32 v34, 16, v108
	v_and_b32_e32 v35, 0xffff0000, v108
	s_waitcnt vmcnt(15)
	v_mov_b32_e32 v36, v240
	v_mov_b32_e32 v37, v241
	v_lshlrev_b32_e32 v22, 16, v36
	v_and_b32_e32 v23, 0xffff0000, v36
	v_lshlrev_b32_e32 v26, 16, v37
	v_and_b32_e32 v27, 0xffff0000, v37
	v_mul_f32_e32 v28, 0xbfb8aa3b, v22
	v_mul_f32_e32 v29, 0xbfb8aa3b, v23
	v_mul_f32_e32 v32, 0xbfb8aa3b, v26
	v_mul_f32_e32 v33, 0xbfb8aa3b, v27
	v_exp_f32_e32 v28, v28
	v_exp_f32_e32 v29, v29
	v_exp_f32_e32 v32, v32
	v_exp_f32_e32 v33, v33
	v_add_f32_e32 v28, 1.0, v28
	v_add_f32_e32 v29, 1.0, v29
	v_add_f32_e32 v32, 1.0, v32
	v_add_f32_e32 v33, 1.0, v33
	v_rcp_f32_e32 v28, v28
	v_rcp_f32_e32 v29, v29
	v_rcp_f32_e32 v32, v32
	v_rcp_f32_e32 v33, v33
	v_pk_mul_f32 v[16:17], v[16:17], v[22:23]
	v_pk_mul_f32 v[18:19], v[18:19], v[26:27]
	v_pk_mul_f32 v[16:17], v[16:17], v[28:29]
	v_pk_mul_f32 v[18:19], v[18:19], v[32:33]
	v_cvt_pk_bf16_f32 v16, v16, v17
	v_cvt_pk_bf16_f32 v17, v18, v19
	global_store_dwordx2 v[24:25], v[16:17], off offset:1120
	v_max_f32_e32 v16, v90, v90
	v_max_f32_e32 v17, v69, v69
	v_max_f32_e32 v38, v17, v16
	v_sub_f32_e32 v16, v69, v38
	v_sub_f32_e32 v17, v90, v38
	v_max_f32_e32 v22, v104, v104
	v_exp_f32_e32 v16, v16
	v_exp_f32_e32 v17, v17
	v_max_f32_e32 v23, v102, v102
	v_max_f32_e32 v22, v38, v22
	v_max_f32_e32 v23, v22, v23
	v_mov_b32_e32 v90, v115
	v_sub_f32_e32 v38, v38, v22
	v_sub_f32_e32 v44, v104, v22
	v_sub_f32_e32 v22, v22, v23
	v_sub_f32_e32 v45, v102, v23
	v_exp_f32_e32 v99, v22
	v_lshl_add_u64 v[22:23], s[16:17], 0, v[20:21]
	v_pk_mul_f32 v[20:21], v[90:91], v[16:17]
	v_exp_f32_e32 v95, v38
	v_pk_fma_f32 v[40:41], v[90:91], v[16:17], v[20:21] op_sel_hi:[1,1,0]
	v_lshlrev_b32_e32 v18, 16, v100
	v_exp_f32_e32 v40, v44
	v_and_b32_e32 v19, 0xffff0000, v100
	v_lshlrev_b32_e32 v24, 16, v101
	v_and_b32_e32 v25, 0xffff0000, v101
	v_lshl_add_u64 v[38:39], v[22:23], 0, s[12:13]
	v_pk_mul_f32 v[42:43], v[20:21], v[18:19] op_sel:[1,0]
	v_pk_mul_f32 v[24:25], v[20:21], v[24:25] op_sel:[1,0]
	v_mov_b32_e32 v22, v95
	v_lshl_add_u64 v[18:19], v[38:39], 0, v[74:75]
	v_pk_fma_f32 v[38:39], v[12:13], v[16:17], v[42:43] op_sel_hi:[1,0,1]
	v_pk_fma_f32 v[14:15], v[14:15], v[16:17], v[24:25] op_sel_hi:[1,0,1]
	v_pk_mul_f32 v[24:25], v[22:23], v[38:39] op_sel_hi:[0,1]
	v_pk_mul_f32 v[38:39], v[22:23], v[14:15] op_sel_hi:[0,1]
	v_pk_mul_f32 v[14:15], v[94:95], v[40:41]
	v_lshlrev_b32_e32 v26, 16, v106
	v_pk_fma_f32 v[40:41], v[94:95], v[40:41], v[14:15] op_sel_hi:[1,1,0]
	v_and_b32_e32 v27, 0xffff0000, v106
	v_exp_f32_e32 v40, v45
	v_lshlrev_b32_e32 v32, 16, v107
	v_and_b32_e32 v33, 0xffff0000, v107
	v_mov_b32_e32 v12, v99
	v_pk_fma_f32 v[24:25], v[14:15], v[26:27], v[24:25] op_sel_hi:[0,1,1]
	v_pk_fma_f32 v[32:33], v[14:15], v[32:33], v[38:39] op_sel_hi:[0,1,1]
	v_pk_mul_f32 v[38:39], v[12:13], v[24:25] op_sel_hi:[0,1]
	v_pk_mul_f32 v[24:25], v[98:99], v[40:41]
	v_lshlrev_b32_e32 v36, 16, v109
	v_add_f32_e32 v13, v24, v25
	v_rcp_f32_e32 v26, v13
	v_and_b32_e32 v37, 0xffff0000, v109
	v_pk_mul_f32 v[32:33], v[12:13], v[32:33] op_sel_hi:[0,1]
	v_pk_fma_f32 v[34:35], v[24:25], v[34:35], v[38:39] op_sel_hi:[0,1,1]
	v_pk_fma_f32 v[32:33], v[24:25], v[36:37], v[32:33] op_sel_hi:[0,1,1]
	v_pk_mul_f32 v[34:35], v[26:27], v[34:35] op_sel_hi:[0,1]
	v_pk_mul_f32 v[32:33], v[26:27], v[32:33] op_sel_hi:[0,1]
	v_lshlrev_b32_e32 v42, 16, v97
	v_and_b32_e32 v43, 0xffff0000, v97
	s_waitcnt vmcnt(15)
	v_mov_b32_e32 v28, v242
	v_mov_b32_e32 v29, v243
	v_lshlrev_b32_e32 v36, 16, v28
	v_and_b32_e32 v37, 0xffff0000, v28
	v_lshlrev_b32_e32 v28, 16, v29
	v_and_b32_e32 v29, 0xffff0000, v29
	v_mul_f32_e32 v13, 0xbfb8aa3b, v36
	v_mul_f32_e32 v17, 0xbfb8aa3b, v37
	v_mul_f32_e32 v23, 0xbfb8aa3b, v28
	v_mul_f32_e32 v27, 0xbfb8aa3b, v29
	v_exp_f32_e32 v13, v13
	v_exp_f32_e32 v17, v17
	v_exp_f32_e32 v23, v23
	v_exp_f32_e32 v27, v27
	v_add_f32_e32 v13, 1.0, v13
	v_add_f32_e32 v17, 1.0, v17
	v_add_f32_e32 v23, 1.0, v23
	v_add_f32_e32 v27, 1.0, v27
	v_rcp_f32_e32 v38, v13
	v_rcp_f32_e32 v39, v17
	v_rcp_f32_e32 v40, v23
	v_rcp_f32_e32 v41, v27
	v_pk_mul_f32 v[34:35], v[34:35], v[36:37]
	v_pk_mul_f32 v[28:29], v[32:33], v[28:29]
	v_pk_mul_f32 v[32:33], v[34:35], v[38:39]
	v_pk_mul_f32 v[28:29], v[28:29], v[40:41]
	v_cvt_pk_bf16_f32 v32, v32, v33
	v_cvt_pk_bf16_f32 v33, v28, v29
	global_store_dwordx2 v[18:19], v[32:33], off offset:1024
	v_lshlrev_b32_e32 v32, 16, v88
	v_and_b32_e32 v33, 0xffff0000, v88
	v_lshlrev_b32_e32 v34, 16, v89
	v_and_b32_e32 v35, 0xffff0000, v89
	v_pk_mul_f32 v[32:33], v[20:21], v[32:33] op_sel:[1,0]
	v_pk_mul_f32 v[34:35], v[20:21], v[34:35] op_sel:[1,0]
	v_pk_fma_f32 v[8:9], v[8:9], v[16:17], v[32:33] op_sel_hi:[1,0,1]
	v_pk_fma_f32 v[10:11], v[10:11], v[16:17], v[34:35] op_sel_hi:[1,0,1]
	v_lshlrev_b32_e32 v36, 16, v92
	v_and_b32_e32 v37, 0xffff0000, v92
	v_lshlrev_b32_e32 v38, 16, v93
	v_and_b32_e32 v39, 0xffff0000, v93
	v_pk_mul_f32 v[8:9], v[22:23], v[8:9] op_sel_hi:[0,1]
	v_pk_mul_f32 v[10:11], v[22:23], v[10:11] op_sel_hi:[0,1]
	v_pk_fma_f32 v[8:9], v[14:15], v[36:37], v[8:9] op_sel_hi:[0,1,1]
	v_pk_fma_f32 v[10:11], v[14:15], v[38:39], v[10:11] op_sel_hi:[0,1,1]
	v_lshlrev_b32_e32 v40, 16, v96
	v_and_b32_e32 v41, 0xffff0000, v96
	v_pk_mul_f32 v[8:9], v[12:13], v[8:9] op_sel_hi:[0,1]
	v_pk_mul_f32 v[10:11], v[12:13], v[10:11] op_sel_hi:[0,1]
	v_pk_fma_f32 v[8:9], v[24:25], v[40:41], v[8:9] op_sel_hi:[0,1,1]
	v_pk_fma_f32 v[10:11], v[24:25], v[42:43], v[10:11] op_sel_hi:[0,1,1]
	v_pk_mul_f32 v[8:9], v[26:27], v[8:9] op_sel_hi:[0,1]
	v_pk_mul_f32 v[10:11], v[26:27], v[10:11] op_sel_hi:[0,1]
	v_lshlrev_b32_e32 v38, 16, v87
	v_and_b32_e32 v39, 0xffff0000, v87
	s_waitcnt vmcnt(15)
	v_mov_b32_e32 v28, v244
	v_mov_b32_e32 v29, v245
	v_lshlrev_b32_e32 v32, 16, v28
	v_and_b32_e32 v33, 0xffff0000, v28
	v_lshlrev_b32_e32 v28, 16, v29
	v_and_b32_e32 v29, 0xffff0000, v29
	v_mul_f32_e32 v13, 0xbfb8aa3b, v32
	v_mul_f32_e32 v17, 0xbfb8aa3b, v33
	v_mul_f32_e32 v23, 0xbfb8aa3b, v28
	v_mul_f32_e32 v27, 0xbfb8aa3b, v29
	v_exp_f32_e32 v13, v13
	v_exp_f32_e32 v17, v17
	v_exp_f32_e32 v23, v23
	v_exp_f32_e32 v27, v27
	v_add_f32_e32 v13, 1.0, v13
	v_add_f32_e32 v17, 1.0, v17
	v_add_f32_e32 v23, 1.0, v23
	v_add_f32_e32 v27, 1.0, v27
	v_rcp_f32_e32 v34, v13
	v_rcp_f32_e32 v35, v17
	v_rcp_f32_e32 v36, v23
	v_rcp_f32_e32 v37, v27
	v_pk_mul_f32 v[8:9], v[8:9], v[32:33]
	v_pk_mul_f32 v[10:11], v[10:11], v[28:29]
	v_pk_mul_f32 v[8:9], v[8:9], v[34:35]
	v_pk_mul_f32 v[10:11], v[10:11], v[36:37]
	v_cvt_pk_bf16_f32 v8, v8, v9
	v_cvt_pk_bf16_f32 v9, v10, v11
	global_store_dwordx2 v[18:19], v[8:9], off offset:1056
	v_lshlrev_b32_e32 v10, 16, v82
	v_and_b32_e32 v11, 0xffff0000, v82
	v_lshlrev_b32_e32 v28, 16, v83
	v_and_b32_e32 v29, 0xffff0000, v83
	v_pk_mul_f32 v[10:11], v[20:21], v[10:11] op_sel:[1,0]
	v_pk_mul_f32 v[28:29], v[20:21], v[28:29] op_sel:[1,0]
	v_pk_fma_f32 v[4:5], v[4:5], v[16:17], v[10:11] op_sel_hi:[1,0,1]
	v_pk_fma_f32 v[6:7], v[6:7], v[16:17], v[28:29] op_sel_hi:[1,0,1]
	v_lshlrev_b32_e32 v32, 16, v84
	v_and_b32_e32 v33, 0xffff0000, v84
	v_lshlrev_b32_e32 v34, 16, v85
	v_and_b32_e32 v35, 0xffff0000, v85
	v_pk_mul_f32 v[4:5], v[22:23], v[4:5] op_sel_hi:[0,1]
	v_pk_mul_f32 v[6:7], v[22:23], v[6:7] op_sel_hi:[0,1]
	v_pk_fma_f32 v[4:5], v[14:15], v[32:33], v[4:5] op_sel_hi:[0,1,1]
	v_pk_fma_f32 v[6:7], v[14:15], v[34:35], v[6:7] op_sel_hi:[0,1,1]
	v_lshlrev_b32_e32 v36, 16, v86
	v_and_b32_e32 v37, 0xffff0000, v86
	v_pk_mul_f32 v[4:5], v[12:13], v[4:5] op_sel_hi:[0,1]
	v_pk_mul_f32 v[6:7], v[12:13], v[6:7] op_sel_hi:[0,1]
	v_pk_fma_f32 v[4:5], v[24:25], v[36:37], v[4:5] op_sel_hi:[0,1,1]
	v_pk_fma_f32 v[6:7], v[24:25], v[38:39], v[6:7] op_sel_hi:[0,1,1]
	v_pk_mul_f32 v[4:5], v[26:27], v[4:5] op_sel_hi:[0,1]
	v_pk_mul_f32 v[6:7], v[26:27], v[6:7] op_sel_hi:[0,1]
	s_waitcnt vmcnt(15)
	v_mov_b32_e32 v8, v246
	v_mov_b32_e32 v9, v247
	v_lshlrev_b32_e32 v10, 16, v8
	v_and_b32_e32 v11, 0xffff0000, v8
	v_lshlrev_b32_e32 v8, 16, v9
	v_and_b32_e32 v9, 0xffff0000, v9
	v_mul_f32_e32 v13, 0xbfb8aa3b, v10
	v_mul_f32_e32 v17, 0xbfb8aa3b, v11
	v_mul_f32_e32 v23, 0xbfb8aa3b, v8
	v_mul_f32_e32 v27, 0xbfb8aa3b, v9
	v_exp_f32_e32 v13, v13
	v_exp_f32_e32 v17, v17
	v_exp_f32_e32 v23, v23
	v_exp_f32_e32 v27, v27
	v_add_f32_e32 v13, 1.0, v13
	v_add_f32_e32 v17, 1.0, v17
	v_add_f32_e32 v23, 1.0, v23
	v_add_f32_e32 v27, 1.0, v27
	v_rcp_f32_e32 v28, v13
	v_rcp_f32_e32 v29, v17
	v_rcp_f32_e32 v32, v23
	v_rcp_f32_e32 v33, v27
	v_pk_mul_f32 v[4:5], v[4:5], v[10:11]
	v_pk_mul_f32 v[6:7], v[6:7], v[8:9]
	v_pk_mul_f32 v[4:5], v[4:5], v[28:29]
	v_pk_mul_f32 v[6:7], v[6:7], v[32:33]
	v_cvt_pk_bf16_f32 v4, v4, v5
	v_cvt_pk_bf16_f32 v5, v6, v7
	global_store_dwordx2 v[18:19], v[4:5], off offset:1088
	v_lshlrev_b32_e32 v6, 16, v76
	v_and_b32_e32 v7, 0xffff0000, v76
	v_pk_mul_f32 v[6:7], v[20:21], v[6:7] op_sel:[1,0]
	v_lshlrev_b32_e32 v8, 16, v77
	v_and_b32_e32 v9, 0xffff0000, v77
	v_pk_fma_f32 v[0:1], v[0:1], v[16:17], v[6:7] op_sel_hi:[1,0,1]
	v_lshlrev_b32_e32 v10, 16, v80
	v_and_b32_e32 v11, 0xffff0000, v80
	v_pk_mul_f32 v[8:9], v[20:21], v[8:9] op_sel:[1,0]
	v_pk_mul_f32 v[0:1], v[22:23], v[0:1] op_sel_hi:[0,1]
	v_pk_fma_f32 v[2:3], v[2:3], v[16:17], v[8:9] op_sel_hi:[1,0,1]
	v_pk_fma_f32 v[0:1], v[14:15], v[10:11], v[0:1] op_sel_hi:[0,1,1]
	v_lshlrev_b32_e32 v28, 16, v81
	v_and_b32_e32 v29, 0xffff0000, v81
	v_pk_mul_f32 v[2:3], v[22:23], v[2:3] op_sel_hi:[0,1]
	v_pk_fma_f32 v[2:3], v[14:15], v[28:29], v[2:3] op_sel_hi:[0,1,1]
	v_lshlrev_b32_e32 v30, 16, v78
	v_and_b32_e32 v31, 0xffff0000, v78
	v_lshlrev_b32_e32 v32, 16, v79
	v_and_b32_e32 v33, 0xffff0000, v79
	v_pk_mul_f32 v[0:1], v[12:13], v[0:1] op_sel_hi:[0,1]
	v_pk_mul_f32 v[2:3], v[12:13], v[2:3] op_sel_hi:[0,1]
	v_pk_fma_f32 v[0:1], v[24:25], v[30:31], v[0:1] op_sel_hi:[0,1,1]
	v_pk_fma_f32 v[2:3], v[24:25], v[32:33], v[2:3] op_sel_hi:[0,1,1]
	v_pk_mul_f32 v[0:1], v[26:27], v[0:1] op_sel_hi:[0,1]
	v_pk_mul_f32 v[2:3], v[26:27], v[2:3] op_sel_hi:[0,1]
	s_waitcnt vmcnt(15)
	v_mov_b32_e32 v4, v248
	v_mov_b32_e32 v5, v249
	v_lshlrev_b32_e32 v6, 16, v4
	v_and_b32_e32 v7, 0xffff0000, v4
	v_lshlrev_b32_e32 v4, 16, v5
	v_and_b32_e32 v5, 0xffff0000, v5
	v_mul_f32_e32 v8, 0xbfb8aa3b, v6
	v_mul_f32_e32 v9, 0xbfb8aa3b, v7
	v_mul_f32_e32 v10, 0xbfb8aa3b, v4
	v_mul_f32_e32 v11, 0xbfb8aa3b, v5
	v_exp_f32_e32 v8, v8
	v_exp_f32_e32 v9, v9
	v_exp_f32_e32 v10, v10
	v_exp_f32_e32 v11, v11
	v_add_f32_e32 v8, 1.0, v8
	v_add_f32_e32 v9, 1.0, v9
	v_add_f32_e32 v10, 1.0, v10
	v_add_f32_e32 v11, 1.0, v11
	v_rcp_f32_e32 v8, v8
	v_rcp_f32_e32 v9, v9
	v_rcp_f32_e32 v10, v10
	v_rcp_f32_e32 v11, v11
	v_pk_mul_f32 v[0:1], v[0:1], v[6:7]
	v_pk_mul_f32 v[2:3], v[2:3], v[4:5]
	v_pk_mul_f32 v[0:1], v[0:1], v[8:9]
	v_pk_mul_f32 v[2:3], v[2:3], v[10:11]
	v_cvt_pk_bf16_f32 v0, v0, v1
	v_cvt_pk_bf16_f32 v1, v2, v3
	global_store_dwordx2 v[18:19], v[0:1], off offset:1120
	s_cbranch_scc0 .LBB0_298
.LBB0_278:
	s_ashr_i32 s14, s23, 4
	s_and_b32 s12, s23, 15
	s_min_u32 s74, s12, 3
	s_ashr_i32 s15, s14, 31
	s_lshl_b64 s[0:1], s[14:15], 12
	s_lshl_b32 s24, s12, 8
	s_or_b32 s16, s0, s24
	s_mov_b32 s17, s1
	s_lshl_b64 s[16:17], s[16:17], 7
	s_add_u32 s18, s66, s16
	s_addc_u32 s19, s67, s17
	s_lshl_b64 s[20:21], s[14:15], 19
	s_add_u32 s15, s68, s20
	s_addc_u32 s21, s69, s21
	s_lshl_b32 s20, s12, 9
	s_add_u32 s20, s15, s20
	s_addc_u32 s21, s21, 0
	v_mov_b32_e32 v65, v121
	v_mov_b32_e32 v69, v121
	v_mov_b32_e32 v67, v121
	v_mov_b32_e32 v71, v121
	v_mov_b32_e32 v73, v121
	v_lshl_add_u64 v[32:33], v[50:51], 0, s[16:17]
	global_load_dwordx4 v[20:23], v[32:33], off
	global_load_dwordx4 v[24:27], v[32:33], off offset:64
	global_load_dwordx4 v[28:31], v[32:33], off offset:2048
	s_nop 0
	global_load_dwordx4 v[32:35], v[32:33], off offset:2112
	v_add_u32_e32 v140, s24, v48
	v_mov_b32_e32 v141, v121
	s_cmp_lg_u32 s12, 0
	v_lshl_add_u64 v[76:77], s[0:1], 0, v[140:141]
	v_mov_b64_e32 v[110:111], 0
	s_cselect_b64 s[18:19], -1, 0
	s_cmp_eq_u32 s12, 0
	v_mov_b64_e32 v[112:113], 0
	v_mov_b64_e32 v[118:119], 0
	v_mov_b64_e32 v[128:129], 0
	v_mov_b64_e32 v[142:143], 0
	v_mov_b32_e32 v132, 0xf149f2ca
	v_mov_b32_e32 v133, 0
	s_cbranch_scc1 .LBB0_280
	v_mad_u64_u32 v[78:79], s[16:17], v76, 24, s[42:43]
	v_mad_i32_i24 v79, v77, 24, v79
	global_load_dwordx2 v[132:133], v[78:79], off
	v_mad_u64_u32 v[78:79], s[16:17], v76, s4, v[52:53]
	v_mad_i32_i24 v79, v77, s4, v79
	global_load_dwordx2 v[142:143], v[78:79], off
	global_load_dwordx2 v[128:129], v[78:79], off offset:32
	global_load_dwordx2 v[118:119], v[78:79], off offset:64
	global_load_dwordx2 v[112:113], v[78:79], off offset:96

.Lown_wd1:
	ds_write_b128 v175, v[200:203]
	ds_write_b128 v123, v[204:207]
	ds_write_b128 v176, v[208:211]
	ds_write_b128 v177, v[212:215]
	ds_write_b128 v182, v[216:219] offset:36864
	ds_write_b128 v183, v[220:223] offset:36864
	ds_write_b128 v185, v[224:227] offset:36864
	ds_write_b128 v186, v[228:231] offset:36864
	v_mov_b32_e32 v2, v121
	v_mov_b32_e32 v3, v121
	v_mov_b32_e32 v0, v121
	v_mov_b32_e32 v1, v121
	v_mov_b64_e32 v[6:7], v[2:3]
	v_mov_b64_e32 v[10:11], v[2:3]
	v_mov_b64_e32 v[14:15], v[2:3]
	v_mov_b64_e32 v[18:19], v[2:3]
	v_mov_b64_e32 v[38:39], v[2:3]
	v_mov_b64_e32 v[42:43], v[2:3]
	v_mov_b64_e32 v[46:47], v[2:3]
	v_mov_b32_e32 v114, v121
	v_mov_b32_e32 v115, v121
	v_mov_b32_e32 v69, 0xf149f2ca
	s_mov_b32 s12, 0
	v_mov_b32_e32 v65, v197
	v_mov_b32_e32 v67, v187
	v_mov_b64_e32 v[4:5], v[0:1]
	v_mov_b64_e32 v[8:9], v[0:1]
	v_mov_b64_e32 v[12:13], v[0:1]
	v_mov_b64_e32 v[16:17], v[0:1]
	v_mov_b64_e32 v[36:37], v[0:1]
	v_mov_b64_e32 v[40:41], v[0:1]
	v_mov_b32_e32 v71, 0xf149f2ca
	v_mov_b64_e32 v[44:45], v[0:1]
	s_waitcnt lgkmcnt(0)
	s_barrier
	s_branch .LBB0_293
